# attention: role A priority 1 during QK+softmax, 0 during its PV (on v60 = role B deferred softmax)
# baseline (speedup 1.0000x reference)
; #define ATT_ISSUE(tilebase, bufbase) do { const unsigned char* _tb = (tilebase); asm volatile("" : "+s"(_tb)); _Pragma("unroll") for (int _i = 0; _i < 6; ++_i) { int _q = wave + 8 * _i; _q = _q > 44 ? 44 : _q; \
;         __builtin_amdgcn_global_load_lds((const unsigned*)(_tb + goff[_i]), (LAS unsigned*)((bufbase) + _q * 1024), 16, 0, 0); } } while (0)
; __device__ __forceinline__ void att_mfma(const Params& P, LAS unsigned char* lds, int wave) {
;     ...
;         for (int kt = 0; kt < ntile; ++kt) {
;             if (kt + 1 < ntile) ATT_ISSUE(kvb + (size_t)(kt + 1) * 327680, lds + bnext * BUF);
;             if (!roleA && kt >= 1 && kt - 1 <= my_last) att_pv(lds + bprev * BUF, vlane, pb, o);
;             if (kt <= my_last) att_qk_sm(lds + bcur * BUF, klane, qf, o, mrun, lrun, pb);
;             if (roleA && kt <= my_last) att_pv(lds + bcur * BUF, vlane, pb, o);
.LBB0_1016:
	s_cmp_lg_u64 s[0:1], 0
	s_cbranch_scc1 .Lv60p_a
	s_setprio 1

; #define LAS __attribute__((address_space(3)))
; #define TR_READ(dst, addr, off) asm volatile("ds_read_b64_tr_b16 %0, %1 offset:%c2" : "=v"(dst) : "v"(addr), "i"(off) : "memory")
; #define TR_WAIT4(n, a, b, c, d) asm volatile("s_waitcnt lgkmcnt(" #n ")" : "+v"(a), "+v"(b), "+v"(c), "+v"(d) :: "memory")
; __device__ __forceinline__ void att_pv(const LAS unsigned char* kb, int vlane, const bf16x8 (&pb)[4], f32x16 (&o)[4]) {
;     constexpr int VP = 320;
;     s16x4 vlo[2][4], vhi[2][4];
;     const unsigned vaddr = (unsigned)(unsigned long)(kb + vlane);
; #pragma unroll
;     for (int d = 0; d < 4; ++d) { TR_READ(vlo[0][d], vaddr, d * 64); TR_READ(vhi[0][d], vaddr, 8 * VP + d * 64); }
; #pragma unroll
;     for (int ks = 0; ks < 4; ++ks) {
;         if (ks < 3) {
; #pragma unroll
;             for (int d = 0; d < 4; ++d) { TR_READ(vlo[(ks + 1) & 1][d], vaddr, ((ks + 1) * 16) * VP + d * 64); TR_READ(vhi[(ks + 1) & 1][d], vaddr, ((ks + 1) * 16 + 8) * VP + d * 64); }
;             TR_WAIT4(8, vlo[ks & 1][0], vlo[ks & 1][1], vlo[ks & 1][2], vlo[ks & 1][3]); TR_WAIT4(8, vhi[ks & 1][0], vhi[ks & 1][1], vhi[ks & 1][2], vhi[ks & 1][3]);
;         } else {
;             TR_WAIT4(0, vlo[ks & 1][0], vlo[ks & 1][1], vlo[ks & 1][2], vlo[ks & 1][3]); TR_WAIT4(0, vhi[ks & 1][0], vhi[ks & 1][1], vhi[ks & 1][2], vhi[ks & 1][3]);
;         }
;         __builtin_amdgcn_sched_barrier(0);
; #pragma unroll
;         for (int d = 0; d < 4; ++d) { const bf16x8 a = __builtin_shufflevector(vlo[ks & 1][d], vhi[ks & 1][d], 0, 1, 2, 3, 4, 5, 6, 7);
;             o[d] = __builtin_amdgcn_mfma_f32_32x32x16_bf16(a, pb[ks], o[d], 0, 0, 0); }
;         __builtin_amdgcn_sched_barrier(0);
;     }
; }
; __device__ __forceinline__ void att_mfma(const Params& P, LAS unsigned char* lds, int wave) {
;     ...
;             if (roleA && kt <= my_last) att_pv(lds + bcur * BUF, vlane, pb, o);
.LBB0_1022:
	s_or_b64 s[4:5], s[0:1], s[16:17]
	s_and_b64 vcc, exec, s[4:5]
	s_cbranch_vccnz .LBB0_1024
	s_setprio 0
	v_add_u32_e32 v80, s78, v222
	v_add_u32_e32 v186, 0x6400, v80
	ds_read_b64_tr_b16 v[80:81], v186 offset:0
	ds_read_b64_tr_b16 v[82:83], v186 offset:2560
	ds_read_b64_tr_b16 v[84:85], v186 offset:64
	ds_read_b64_tr_b16 v[86:87], v186 offset:2624
	ds_read_b64_tr_b16 v[88:89], v186 offset:128
	ds_read_b64_tr_b16 v[90:91], v186 offset:2688
	ds_read_b64_tr_b16 v[92:93], v186 offset:192
	ds_read_b64_tr_b16 v[94:95], v186 offset:2752
	ds_read_b64_tr_b16 v[170:171], v186 offset:5120
	ds_read_b64_tr_b16 v[172:173], v186 offset:7680
	ds_read_b64_tr_b16 v[174:175], v186 offset:5184
	ds_read_b64_tr_b16 v[176:177], v186 offset:7744
	ds_read_b64_tr_b16 v[178:179], v186 offset:5248
	ds_read_b64_tr_b16 v[180:181], v186 offset:7808
	ds_read_b64_tr_b16 v[182:183], v186 offset:5312
	ds_read_b64_tr_b16 v[184:185], v186 offset:7872
	s_waitcnt lgkmcnt(8)
	v_mfma_f32_32x32x16_bf16 v[48:63], v[80:83], v[76:79], v[48:63]
	v_mfma_f32_32x32x16_bf16 v[32:47], v[84:87], v[76:79], v[32:47]
	v_mfma_f32_32x32x16_bf16 v[16:31], v[88:91], v[76:79], v[16:31]
	v_mfma_f32_32x32x16_bf16 v[0:15], v[92:95], v[76:79], v[0:15]
	ds_read_b64_tr_b16 v[80:81], v186 offset:10240
	ds_read_b64_tr_b16 v[82:83], v186 offset:12800
	ds_read_b64_tr_b16 v[84:85], v186 offset:10304
	ds_read_b64_tr_b16 v[86:87], v186 offset:12864
	ds_read_b64_tr_b16 v[88:89], v186 offset:10368
	ds_read_b64_tr_b16 v[90:91], v186 offset:12928
	ds_read_b64_tr_b16 v[92:93], v186 offset:10432
	ds_read_b64_tr_b16 v[94:95], v186 offset:12992
	s_waitcnt lgkmcnt(8)
	v_mfma_f32_32x32x16_bf16 v[48:63], v[170:173], v[72:75], v[48:63]
	v_mfma_f32_32x32x16_bf16 v[32:47], v[174:177], v[72:75], v[32:47]
	v_mfma_f32_32x32x16_bf16 v[16:31], v[178:181], v[72:75], v[16:31]
	v_mfma_f32_32x32x16_bf16 v[0:15], v[182:185], v[72:75], v[0:15]
	ds_read_b64_tr_b16 v[170:171], v186 offset:15360
	ds_read_b64_tr_b16 v[172:173], v186 offset:17920
	ds_read_b64_tr_b16 v[174:175], v186 offset:15424
	ds_read_b64_tr_b16 v[176:177], v186 offset:17984
	ds_read_b64_tr_b16 v[178:179], v186 offset:15488
	ds_read_b64_tr_b16 v[180:181], v186 offset:18048
	ds_read_b64_tr_b16 v[182:183], v186 offset:15552
	ds_read_b64_tr_b16 v[184:185], v186 offset:18112
	s_waitcnt lgkmcnt(8)
	v_mfma_f32_32x32x16_bf16 v[48:63], v[80:83], v[68:71], v[48:63]
	v_mfma_f32_32x32x16_bf16 v[32:47], v[84:87], v[68:71], v[32:47]
	v_mfma_f32_32x32x16_bf16 v[16:31], v[88:91], v[68:71], v[16:31]
	v_mfma_f32_32x32x16_bf16 v[0:15], v[92:95], v[68:71], v[0:15]
	s_waitcnt lgkmcnt(0)
	v_mfma_f32_32x32x16_bf16 v[48:63], v[170:173], v[64:67], v[48:63]
	v_mfma_f32_32x32x16_bf16 v[32:47], v[174:177], v[64:67], v[32:47]
	v_mfma_f32_32x32x16_bf16 v[16:31], v[178:181], v[64:67], v[16:31]
	v_mfma_f32_32x32x16_bf16 v[0:15], v[182:185], v[64:67], v[0:15]
